# P3 prompt attention: cross-row running max via v_permlane16/32_swap, the two lgkmcnt(0) after the former bpermutes removed
# speedup vs baseline: 1.0177x; 1.0055x over previous
.LBB0_1675:
	v_max3_f32 v70, v0, s80, v1
	v_max3_f32 v70, v70, v2, v3
	v_max3_f32 v70, v70, v4, v5
	v_max3_f32 v70, v70, v6, v7
	v_max3_f32 v70, v70, v8, v9
	v_max3_f32 v70, v70, v10, v11
	v_cmp_lt_i32_e32 vcc, v87, v88
	v_max3_f32 v70, v70, v12, v13
	v_max3_f32 v70, v70, v14, v15
	v_cndmask_b32_e32 v71, v133, v87, vcc
	v_lshlrev_b32_e32 v71, 2, v71
	v_cmp_lt_i32_e32 vcc, v89, v88
	v_mov_b32_e32 v71, v70
	s_nop 1
	v_permlane16_swap_b32_e32 v71, v70
	v_max_f32_e32 v70, v70, v71
	v_cndmask_b32_e32 v71, v133, v89, vcc
	v_lshlrev_b32_e32 v71, 2, v71
	v_mov_b32_e32 v71, v70
	s_nop 1
	v_permlane32_swap_b32_e32 v71, v70
	v_max3_f32 v71, v92, v70, v71
	v_cmp_neq_f32_e32 vcc, s80, v71
	s_nop 1
	v_cndmask_b32_e32 v100, 0, v71, vcc
	v_sub_f32_e32 v0, v0, v100
	v_sub_f32_e32 v1, v1, v100
	v_sub_f32_e32 v70, v92, v100
	v_exp_f32_e32 v92, v0
	v_exp_f32_e32 v93, v1
	v_sub_f32_e32 v0, v2, v100
	v_exp_f32_e32 v94, v0
	v_sub_f32_e32 v0, v3, v100
	v_exp_f32_e32 v95, v0
	v_sub_f32_e32 v1, v4, v100
	v_add_f32_e32 v0, 0, v92
	v_exp_f32_e32 v96, v1
	v_sub_f32_e32 v1, v5, v100
	v_add_f32_e32 v0, v93, v0
	v_exp_f32_e32 v97, v1
	v_sub_f32_e32 v1, v6, v100
	v_add_f32_e32 v0, v94, v0
	v_exp_f32_e32 v98, v1
	v_sub_f32_e32 v1, v7, v100
	v_add_f32_e32 v0, v95, v0
	v_exp_f32_e32 v7, v1
	v_add_f32_e32 v0, v96, v0
	v_add_f32_e32 v0, v97, v0
	v_add_f32_e32 v0, v98, v0
	v_add_f32_e32 v101, v7, v0
	v_sub_f32_e32 v0, v8, v100
	v_exp_f32_e32 v102, v0
	v_sub_f32_e32 v0, v9, v100
	v_exp_f32_e32 v103, v0
	v_sub_f32_e32 v0, v10, v100
	v_exp_f32_e32 v70, v70
	v_exp_f32_e32 v104, v0
	v_sub_f32_e32 v0, v11, v100
	v_exp_f32_e32 v105, v0
	v_sub_f32_e32 v0, v12, v100
	v_exp_f32_e32 v106, v0
	v_sub_f32_e32 v0, v13, v100
	v_exp_f32_e32 v107, v0
	v_pk_mul_f32 v[2:3], v[54:55], v[70:71] op_sel_hi:[1,0]
	v_pk_mul_f32 v[0:1], v[52:53], v[70:71] op_sel_hi:[1,0]
	v_cvt_pk_bf16_f32 v4, v92, v93
	v_cvt_pk_bf16_f32 v5, v94, v95
	v_cvt_pk_bf16_f32 v6, v96, v97
	v_cvt_pk_bf16_f32 v7, v98, v7
	s_waitcnt lgkmcnt(0)
	v_sub_f32_e32 v12, v14, v100
	s_nop 0
	v_mfma_f32_16x16x32_bf16 v[0:3], v[140:143], v[4:7], v[0:3]
	v_mul_f32_e64 v50, v50, v70
	v_mul_f32_e64 v51, v51, v70
	v_pk_mul_f32 v[48:49], v[48:49], v[70:71] op_sel_hi:[1,0]
	v_exp_f32_e32 v96, v12
	v_pk_mul_f32 v[12:13], v[44:45], v[70:71] op_sel_hi:[1,0]
	v_mfma_f32_16x16x32_bf16 v[48:51], v[144:147], v[4:7], v[48:51]
	v_sub_f32_e32 v92, v15, v100
	v_pk_mul_f32 v[14:15], v[46:47], v[70:71] op_sel_hi:[1,0]
	v_pk_mul_f32 v[26:27], v[26:27], v[70:71] op_sel_hi:[1,0]
	v_pk_mul_f32 v[24:25], v[24:25], v[70:71] op_sel_hi:[1,0]
	v_mfma_f32_16x16x32_bf16 v[12:15], v[148:151], v[4:7], v[12:15]
	v_exp_f32_e32 v97, v92
	v_mfma_f32_16x16x32_bf16 v[4:7], v[152:155], v[4:7], v[24:27]
	s_waitcnt lgkmcnt(0)
	v_cvt_pk_bf16_f32 v8, v102, v103
	v_cvt_pk_bf16_f32 v9, v104, v105
	v_cvt_pk_bf16_f32 v10, v106, v107
	v_cvt_pk_bf16_f32 v11, v96, v97
	s_nop 0
	v_mfma_f32_16x16x32_bf16 v[52:55], v[156:159], v[8:11], v[0:3]
	s_nop 2
	v_add_f32_e32 v0, v102, v101
	v_add_f32_e32 v0, v103, v0
	v_add_f32_e32 v0, v104, v0
	v_add_f32_e32 v0, v105, v0
	v_add_f32_e32 v0, v106, v0
	v_add_f32_e32 v0, v107, v0
	v_mfma_f32_16x16x32_bf16 v[48:51], v[160:163], v[8:11], v[48:51]
	v_add_f32_e32 v0, v96, v0
	v_add_f32_e32 v0, v97, v0
	v_fmac_f32_e32 v0, v83, v70
	v_mfma_f32_16x16x32_bf16 v[44:47], v[164:167], v[8:11], v[12:15]
	v_mov_b32_e32 v83, v0
	v_mov_b32_e32 v92, v71
	v_mfma_f32_16x16x32_bf16 v[24:27], v[168:171], v[8:11], v[4:7]

.LBB0_1685:
	v_max3_f32 v68, v0, s80, v1
	v_max3_f32 v68, v68, v2, v3
	v_max3_f32 v68, v68, v4, v5
	v_max3_f32 v68, v68, v6, v7
	v_max3_f32 v68, v68, v8, v9
	v_max3_f32 v68, v68, v10, v11
	v_cmp_lt_i32_e32 vcc, v87, v88
	v_max3_f32 v68, v68, v12, v13
	v_max3_f32 v68, v68, v14, v15
	v_cndmask_b32_e32 v69, v133, v87, vcc
	v_lshlrev_b32_e32 v69, 2, v69
	v_cmp_lt_i32_e32 vcc, v89, v88
	v_mov_b32_e32 v69, v68
	s_nop 1
	v_permlane16_swap_b32_e32 v69, v68
	v_max_f32_e32 v68, v68, v69
	v_cndmask_b32_e32 v69, v133, v89, vcc
	v_lshlrev_b32_e32 v69, 2, v69
	v_mov_b32_e32 v69, v68
	s_nop 1
	v_permlane32_swap_b32_e32 v69, v68
	v_max3_f32 v69, v92, v68, v69
	v_cmp_neq_f32_e32 vcc, s80, v69
	s_nop 1
	v_cndmask_b32_e32 v100, 0, v69, vcc
	v_sub_f32_e32 v0, v0, v100
	v_sub_f32_e32 v1, v1, v100
	v_sub_f32_e32 v68, v92, v100
	v_exp_f32_e32 v92, v0
	v_exp_f32_e32 v93, v1
	v_sub_f32_e32 v0, v2, v100
	v_exp_f32_e32 v94, v0
	v_sub_f32_e32 v0, v3, v100
	v_exp_f32_e32 v95, v0
	v_sub_f32_e32 v1, v4, v100
	v_add_f32_e32 v0, 0, v92
	v_exp_f32_e32 v96, v1
	v_sub_f32_e32 v1, v5, v100
	v_add_f32_e32 v0, v93, v0
	v_exp_f32_e32 v97, v1
	v_sub_f32_e32 v1, v6, v100
	v_add_f32_e32 v0, v94, v0
	v_exp_f32_e32 v98, v1
	v_sub_f32_e32 v1, v7, v100
	v_add_f32_e32 v0, v95, v0
	v_exp_f32_e32 v7, v1
	v_add_f32_e32 v0, v96, v0
	v_add_f32_e32 v0, v97, v0
	v_add_f32_e32 v0, v98, v0
	v_add_f32_e32 v101, v7, v0
	v_sub_f32_e32 v0, v8, v100
	v_exp_f32_e32 v102, v0
	v_sub_f32_e32 v0, v9, v100
	v_exp_f32_e32 v103, v0
	v_sub_f32_e32 v0, v10, v100
	v_exp_f32_e32 v68, v68
	v_exp_f32_e32 v104, v0
	v_sub_f32_e32 v0, v11, v100
	v_exp_f32_e32 v105, v0
	v_sub_f32_e32 v0, v12, v100
	v_exp_f32_e32 v106, v0
	v_sub_f32_e32 v0, v13, v100
	v_exp_f32_e32 v107, v0
	v_pk_mul_f32 v[2:3], v[54:55], v[68:69] op_sel_hi:[1,0]
	v_pk_mul_f32 v[0:1], v[52:53], v[68:69] op_sel_hi:[1,0]
	v_cvt_pk_bf16_f32 v4, v92, v93
	v_cvt_pk_bf16_f32 v5, v94, v95
	v_cvt_pk_bf16_f32 v6, v96, v97
	v_cvt_pk_bf16_f32 v7, v98, v7
	s_waitcnt lgkmcnt(0)
	v_sub_f32_e32 v12, v14, v100
	s_nop 0
	v_mfma_f32_16x16x32_bf16 v[0:3], v[140:143], v[4:7], v[0:3]
	v_mul_f32_e64 v50, v50, v68
	v_mul_f32_e64 v51, v51, v68
	v_pk_mul_f32 v[48:49], v[48:49], v[68:69] op_sel_hi:[1,0]
	v_exp_f32_e32 v96, v12
	v_pk_mul_f32 v[12:13], v[44:45], v[68:69] op_sel_hi:[1,0]
	v_mfma_f32_16x16x32_bf16 v[48:51], v[144:147], v[4:7], v[48:51]
	v_sub_f32_e32 v92, v15, v100
	v_pk_mul_f32 v[14:15], v[46:47], v[68:69] op_sel_hi:[1,0]
	v_pk_mul_f32 v[26:27], v[26:27], v[68:69] op_sel_hi:[1,0]
	v_pk_mul_f32 v[24:25], v[24:25], v[68:69] op_sel_hi:[1,0]
	v_mfma_f32_16x16x32_bf16 v[12:15], v[148:151], v[4:7], v[12:15]
	v_exp_f32_e32 v97, v92
	v_mfma_f32_16x16x32_bf16 v[4:7], v[152:155], v[4:7], v[24:27]
	s_waitcnt lgkmcnt(0)
	v_cvt_pk_bf16_f32 v8, v102, v103
	v_cvt_pk_bf16_f32 v9, v104, v105
	v_cvt_pk_bf16_f32 v10, v106, v107
	v_cvt_pk_bf16_f32 v11, v96, v97
	s_nop 0
	v_mfma_f32_16x16x32_bf16 v[52:55], v[156:159], v[8:11], v[0:3]
	s_nop 2
	v_add_f32_e32 v0, v102, v101
	v_add_f32_e32 v0, v103, v0
	v_add_f32_e32 v0, v104, v0
	v_add_f32_e32 v0, v105, v0
	v_add_f32_e32 v0, v106, v0
	v_add_f32_e32 v0, v107, v0
	v_mfma_f32_16x16x32_bf16 v[48:51], v[160:163], v[8:11], v[48:51]
	v_add_f32_e32 v0, v96, v0
	v_add_f32_e32 v0, v97, v0
	v_fmac_f32_e32 v0, v83, v68
	v_mfma_f32_16x16x32_bf16 v[44:47], v[164:167], v[8:11], v[12:15]
	v_mov_b32_e32 v83, v0
	v_mov_b32_e32 v92, v69
	v_mfma_f32_16x16x32_bf16 v[24:27], v[168:171], v[8:11], v[4:7]
